# P0: weight-transpose work rebalanced (35 per adaLN workgroup, 17 per S5-matrix workgroup) after the adaLN unit got faster
# speedup vs baseline: 1.0124x; 1.0102x over previous
.LBB0_109:
	s_cmpk_lg_i32 s28, 0x100
	s_cselect_b64 s[6:7], -1, 0
	s_cmpk_eq_i32 s28, 0x100
	s_cselect_b64 s[2:3], -1, 0
	s_and_b64 vcc, exec, s[2:3]
	s_cbranch_vccz .LBB0_111
	s_cmpk_lt_i32 s26, 0xc0
	s_cselect_b32 s18, 35, 17
	s_cbranch_execz .LBB0_112
	s_branch .LBB0_113

.LBB0_113:
	s_cmpk_lt_i32 s26, 0xc0
	s_cselect_b64 s[0:1], -1, 0
	s_cmpk_gt_i32 s26, 0xbf
	s_cselect_b64 s[4:5], -1, 0
	s_add_i32 s19, s26, 0x1980
	s_or_b64 s[6:7], s[0:1], s[6:7]
	s_and_b64 s[6:7], s[6:7], exec
	s_cselect_b32 s6, s26, s19
	s_cmp_gt_i32 s18, 0
	v_readlane_b32 s56, v254, 7
	s_cselect_b32 s7, s6, 0x1e80
	v_mov_b32_e32 v5, 0
	v_readlane_b32 s94, v254, 5
	v_readlane_b32 s86, v254, 3
	v_readlane_b32 s63, v254, 14
	s_cmpk_gt_i32 s7, 0x1e7f
	v_mov_b32_e32 v4, v5
	v_mov_b32_e32 v3, v5
	v_mov_b32_e32 v2, v5
	v_mov_b32_e32 v9, v5
	v_mov_b32_e32 v8, v5
	v_mov_b32_e32 v7, v5
	v_mov_b32_e32 v6, v5
	v_readlane_b32 s95, v254, 6
	v_readlane_b32 s87, v254, 4
	v_readlane_b32 s68, v254, 19
	v_readlane_b32 s69, v254, 20
	v_readlane_b32 s70, v254, 21
	v_readlane_b32 s71, v254, 22
	v_readlane_b32 s63, v254, 2
	v_readlane_b32 s57, v254, 8
	v_readlane_b32 s58, v254, 9
	v_readlane_b32 s59, v254, 10
	v_readlane_b32 s60, v254, 11
	v_readlane_b32 s61, v254, 12
	v_readlane_b32 s62, v254, 13
	v_readlane_b32 s64, v254, 15
	v_readlane_b32 s65, v254, 16
	v_readlane_b32 s66, v254, 17
	v_readlane_b32 s67, v254, 18
	s_cbranch_scc1 .LBB0_123
	s_mul_hi_i32 s6, s7, 0x4325c53f
	s_lshr_b32 s8, s6, 31
	s_ashr_i32 s6, s6, 10
	s_add_i32 s6, s6, s8
	s_mul_i32 s8, s6, 0xf40
	s_sub_i32 s14, s7, s8
	s_cmpk_gt_i32 s14, 0xaff
	s_cbranch_scc0 .LBB0_117
	s_ashr_i32 s7, s6, 31
	s_lshl_b32 s12, s14, 6
	s_cmpk_gt_u32 s14, 0xeff
	s_cbranch_scc0 .LBB0_118
	s_add_i32 s8, s14, 0xfffff100
	s_lshr_b32 s8, s8, 3
	s_lshl_b64 s[10:11], s[6:7], 20
	s_add_u32 s10, s36, s10
	s_mov_b32 s9, 0
	s_addc_u32 s11, s37, s11
	s_lshl_b64 s[8:9], s[8:9], 17
	s_add_u32 s8, s10, s8
	s_addc_u32 s9, s11, s9
	s_and_b32 s10, s12, 0x1c0
	s_lshl_b32 s10, s10, 2
	s_add_u32 s8, s8, s10
	s_addc_u32 s9, s9, 0
	s_mov_b64 s[10:11], 0x200
	s_cbranch_execz .LBB0_119
	s_branch .LBB0_120

.LBB0_123:
	v_cndmask_b32_e64 v10, 0, 1, s[2:3]
	s_movk_i32 s8, 0x1e80
	s_cmp_lt_i32 s18, 2
	v_cmp_ne_u32_e64 s[2:3], 1, v10
	s_cbranch_scc1 .LBB0_132
	s_and_b64 vcc, exec, s[2:3]
	s_cbranch_vccnz .LBB0_127
	s_and_b64 vcc, exec, s[4:5]
	s_cbranch_vccz .LBB0_128
	s_add_i32 s8, s26, 0x19c0
	s_cbranch_execz .LBB0_129
	s_branch .LBB0_130

.LBB0_143:
	s_and_b64 vcc, exec, s[2:3]
	s_cbranch_vccnz .LBB0_146
	s_and_b64 vcc, exec, s[4:5]
	s_cbranch_vccz .LBB0_147
	s_add_i32 s8, s26, 0x1a00
	s_cbranch_execz .LBB0_148
	s_branch .LBB0_149
